# grid barrier: XCC leaders add to the cross-XCC counter without return and every workgroup polls that counter (no per-XCC generation words, one round trip less)
# speedup vs baseline: 1.0047x; 1.0047x over previous
.LBB0_517:
	s_cmp_lt_i32 s24, 2
	s_cselect_b64 s[0:1], -1, 0
	s_xor_b64 s[6:7], s[6:7], -1
	s_or_b64 s[0:1], s[0:1], s[6:7]
	s_and_b64 vcc, exec, s[0:1]
	s_cbranch_vccnz .LBB0_5
	s_cmp_lg_u32 s24, 2
	s_mov_b64 s[6:7], -1
	s_cbranch_scc0 .LBB0_526
	s_waitcnt vmcnt(0) lgkmcnt(0)
	v_readlane_b32 s28, v254, 41
	v_readlane_b32 s29, v254, 42
	v_readlane_b32 s0, v254, 28
	s_load_dwordx2 s[28:29], s[28:29], 0x120
	s_add_i32 s13, s0, 1
	s_waitcnt vmcnt(0)
	s_barrier
	s_mov_b64 s[6:7], exec
	v_readlane_b32 s0, v254, 29
	v_readlane_b32 s1, v254, 30
	s_and_b64 s[0:1], s[6:7], s[0:1]
	s_mov_b64 exec, s[0:1]
	s_cbranch_execz .LBB0_525
	s_getreg_b32 s8, hwreg(HW_REG_XCC_ID, 0, 4)
	s_and_b32 s8, s8, 7
	s_lshr_b32 s9, s54, 3
	v_mov_b32_e32 v1, 1
	s_mul_i32 s9, s9, s13
	s_lshl_b32 s11, s8, 4
	s_lshl_b32 s18, s8, 3
	s_add_u32 s18, s18, 0x80
	v_mov_b32_e32 v3, s11
	v_mov_b32_e32 v5, s18
	s_waitcnt lgkmcnt(0)
	s_add_u32 s0, s28, 0x198000
	s_addc_u32 s1, s29, 0
	global_atomic_add v3, v3, v1, s[0:1] sc0
	s_mov_b32 s20, 0
	s_lshl_b32 s21, s13, 3
	s_waitcnt vmcnt(0)
	v_add_u32_e32 v3, 1, v3
	v_cmp_eq_u32_e32 vcc, s9, v3
	s_cbranch_vccz .Lxb_early
	buffer_wbl2 sc1
	s_waitcnt vmcnt(0)
	global_atomic_add v2, v1, s[0:1] offset:192
.Lxb_early:
.Lxb_fspin:
	global_load_dword v3, v2, s[0:1] offset:192 sc1
	s_waitcnt vmcnt(0)
	v_cmp_le_u32_e32 vcc, s21, v3
	s_cbranch_vccnz .Lxb_facq
	s_sleep 1
	s_add_u32 s20, s20, 1
	s_cmp_lt_u32 s20, 0x2000
	s_cbranch_scc1 .Lxb_fspin
	v_mov_b32_e32 v1, 0x100000
	global_atomic_add v2, v1, s[0:1] offset:192
